# fused epilogues: the four RMS-exchange slot loads issued together (were three dependent sc1 round trips per tile)
# speedup vs baseline: 1.0023x; 1.0023x over previous
; __device__ __forceinline__ void panel_rms(const f32x4 (&v)[2][2][4][2], int pm, int pn, int wr, int wc, int fr, int fq, LAS unsigned char* xl, int wid, int lane, float* slots, unsigned* cnt) {
;     ...
;     if (lane < 32) { float s = 0.f;
; #pragma unroll
;         for (int t = 0; t < 4; ++t) s += __uint_as_float(__hip_atomic_load(sl + t, __ATOMIC_RELAXED, __HIP_MEMORY_SCOPE_AGENT));
;         S[row] = rsqrtf(s * (1.f / DM) + EPS); }
.LBB0_98:
	s_waitcnt vmcnt(0) lgkmcnt(0)
	s_barrier
	s_and_saveexec_b64 s[12:13], s[6:7]
	s_cbranch_execz .LBB0_100
	global_load_dword v130, v[128:129], off sc1
	global_load_dword v131, v[128:129], off offset:4 sc1
	global_load_dword v132, v[128:129], off offset:8 sc1
	global_load_dword v133, v[128:129], off offset:12 sc1
	s_waitcnt vmcnt(0)
	v_add_f32_e32 v130, 0, v130
	v_add_f32_e32 v130, v130, v131
	v_add_f32_e32 v130, v130, v132
	v_add_f32_e32 v128, v130, v133
	v_fmamk_f32 v128, v128, 0x3a800000, v158
	v_cmp_gt_f32_e32 vcc, s55, v128
	v_mul_f32_e32 v129, 0x4b800000, v128
	s_nop 0
	v_cndmask_b32_e32 v128, v128, v129, vcc
	v_rsq_f32_e32 v128, v128
	s_nop 0
	v_mul_f32_e32 v129, 0x45800000, v128
	v_cndmask_b32_e32 v128, v128, v129, vcc
	ds_write_b32 v196, v128

; __device__ __forceinline__ void panel_rms(const f32x4 (&v)[2][2][4][2], int pm, int pn, int wr, int wc, int fr, int fq, LAS unsigned char* xl, int wid, int lane, float* slots, unsigned* cnt) {
;     ...
;     if (lane < 32) { float s = 0.f;
; #pragma unroll
;         for (int t = 0; t < 4; ++t) s += __uint_as_float(__hip_atomic_load(sl + t, __ATOMIC_RELAXED, __HIP_MEMORY_SCOPE_AGENT));
;         S[row] = rsqrtf(s * (1.f / DM) + EPS); }
.LBB0_285:
	s_waitcnt vmcnt(0) lgkmcnt(0)
	s_barrier
	s_and_saveexec_b64 s[68:69], s[6:7]
	s_cbranch_execz .LBB0_287
	global_load_dword v140, v[138:139], off sc1
	global_load_dword v141, v[138:139], off offset:4 sc1
	global_load_dword v142, v[138:139], off offset:8 sc1
	global_load_dword v143, v[138:139], off offset:12 sc1
	s_waitcnt vmcnt(0)
	v_add_f32_e32 v140, 0, v140
	v_add_f32_e32 v140, v140, v141
	v_add_f32_e32 v140, v140, v142
	v_add_f32_e32 v138, v140, v143
	v_fmamk_f32 v138, v138, 0x3a800000, v158
	v_cmp_gt_f32_e32 vcc, s55, v138
	v_mul_f32_e32 v139, 0x4b800000, v138
	s_nop 0
	v_cndmask_b32_e32 v138, v138, v139, vcc
	v_rsq_f32_e32 v138, v138
	s_nop 0
	v_mul_f32_e32 v139, 0x45800000, v138
	v_cndmask_b32_e32 v138, v138, v139, vcc
	ds_write_b32 v174, v138
